# GEMM K loops: flips deleted, static s_setprio 1 for waves 4-7 (other half)
# baseline (speedup 1.0000x reference)
;     __device__ bool next(int i, Unit& u) const {
;         const long L = (long)i * G + c; if (L >= nwg) return false;
;         int wgid = (int)L; { const int q = nwg / NXCD, r = nwg % NXCD, xcd = wgid % NXCD, off = wgid / NXCD; wgid = (xcd < r ? xcd * (q + 1) : r * (q + 1) + (xcd - r) * q) + off; }
;         const int nig = WGM * nN, gid = wgid / nig, fm = gid * WGM, gsz = (nM - fm) < WGM ? (nM - fm) : WGM;
;         u.pm = fm + ((wgid % nig) % gsz); u.pn = (wgid % nig) / gsz; return true;
;     }
; template <class Epi>
; __device__ __forceinline__ void gemm_phase(LAS unsigned char* lds, const Gemm g, const StaticOrder& S, const Epi& E) {
;     ...
;         const bool has_next = S.next(ui + 1, nxt);
;         const char* nA = has_next ? (const char*)g.A + (size_t)nxt.pm * tstepA : cA; const char* nB = has_next ? (const char*)g.Bt + (size_t)nxt.pn * tstepB : cB;
.LBB0_201:
	s_and_b64 vcc, exec, s[0:1]
	s_mov_b32 s43, s10
	s_mov_b32 s18, s12
	s_mov_b64 s[22:23], s[16:17]
	s_mov_b64 s[20:21], s[14:15]
	s_cbranch_vccnz .LBB0_211
.LBB0_202:
	v_readfirstlane_b32 s98, v152
	s_nop 3
	s_cmp_ge_u32 s98, 0x100
	s_cbranch_scc0 .Lknf0_skip
	s_setprio 1
.Lknf0_skip:
	s_add_i32 s35, s35, 1
	s_mul_i32 s0, s35, s38
	s_mul_hi_u32 s1, s35, s92
	s_add_i32 s1, s1, s0
	s_mul_i32 s0, s35, s92
	s_add_u32 s14, s0, s93
	s_addc_u32 s15, s1, s28
	v_cmp_gt_i64_e64 s[0:1], s[14:15], v[144:145]
	s_and_b64 vcc, exec, s[0:1]
	s_cbranch_vccnz .LBB0_204
	s_lshr_b32 s10, s14, 3
	s_mov_b32 s13, 0
	s_sub_u32 s11, s10, 0xa8
	s_cmp_ge_u32 s10, 0xa8
	s_cselect_b32 s10, s11, s10
	s_addc_u32 s13, s13, 0
	s_sub_u32 s11, s10, 0xa8
	s_cmp_ge_u32 s10, 0xa8
	s_cselect_b32 s10, s11, s10
	s_addc_u32 s13, s13, 0
	s_sub_u32 s11, s10, 0xa8
	s_cmp_ge_u32 s10, 0xa8
	s_cselect_b32 s10, s11, s10
	s_addc_u32 s13, s13, 0
	s_and_b32 s12, s14, 7
	s_lshl_b32 s12, s12, 2
	s_add_i32 s12, s12, s13
	s_lshl_b32 s12, s12, 3
	s_and_b32 s13, s10, 7
	s_add_i32 s12, s12, s13
	s_lshr_b32 s10, s10, 3

;     __device__ bool next(int i, Unit& u) const {
;         const long L = (long)i * G + c; if (L >= nwg) return false;
;         int wgid = (int)L; { const int q = nwg / NXCD, r = nwg % NXCD, xcd = wgid % NXCD, off = wgid / NXCD; wgid = (xcd < r ? xcd * (q + 1) : r * (q + 1) + (xcd - r) * q) + off; }
;         const int nig = WGM * nN, gid = wgid / nig, fm = gid * WGM, gsz = (nM - fm) < WGM ? (nM - fm) : WGM;
;         u.pm = fm + ((wgid % nig) % gsz); u.pn = (wgid % nig) / gsz; return true;
;     }
; template <class Epi>
; __device__ __forceinline__ void gemm_phase(LAS unsigned char* lds, const Gemm g, const StaticOrder& S, const Epi& E) {
;     ...
;         const bool has_next = S.next(ui + 1, nxt);
;         const char* nA = has_next ? (const char*)g.A + (size_t)nxt.pm * tstepA : cA; const char* nB = has_next ? (const char*)g.Bt + (size_t)nxt.pn * tstepB : cB;
.LBB0_674:
	s_or_b64 exec, exec, s[4:5]
	s_and_b64 vcc, exec, s[2:3]
	s_mov_b32 s10, s16
	s_mov_b32 s12, s44
	s_mov_b64 s[22:23], s[20:21]
	s_mov_b64 s[24:25], s[18:19]
	s_cbranch_vccnz .LBB0_701
.LBB0_675:
	v_readfirstlane_b32 s98, v152
	s_nop 3
	s_cmp_ge_u32 s98, 0x100
	s_cbranch_scc0 .Lknf1_skip
	s_setprio 1
.Lknf1_skip:
	s_add_i32 s33, s33, 1
	s_mul_i32 s2, s33, s40
	s_mul_hi_u32 s3, s33, s92
	s_add_i32 s3, s3, s2
	s_mul_i32 s2, s33, s92
	s_add_u32 s18, s2, s93
	s_addc_u32 s19, s3, s41
	v_cmp_gt_i64_e64 s[2:3], s[18:19], v[168:169]
	v_cmp_lt_i64_e64 s[4:5], s[18:19], v[166:167]
	s_and_b64 vcc, exec, s[2:3]
	s_cbranch_vccnz .LBB0_681
	s_ashr_i32 s16, s18, 31
	s_lshr_b32 s16, s16, 29
	s_add_i32 s19, s18, s16
	s_and_b32 s16, s19, -8
	s_sub_i32 s18, s18, s16
	s_cmp_gt_i32 s18, -1
	s_mov_b64 s[16:17], -1
	s_cbranch_scc0 .LBB0_678
	s_lshl_b32 s20, s18, 7
	s_mov_b64 s[16:17], 0

; #define PG8_STAGE(bufoff, gbase, voff) do { _Pragma("unroll") for (int _i = 0; _i < 2; ++_i) \
;         __builtin_amdgcn_global_load_lds((const unsigned*)((const char*)(gbase) + (voff)[_i]), (LAS unsigned*)(lds + (bufoff) + ldsw + _i * 8192), 16, 0, 0); } while (0)
; #define PG8_WAIT_V(n) asm volatile("s_waitcnt vmcnt(" #n ")" ::: "memory")
; #define PG8_BAR __builtin_amdgcn_s_barrier()
; template <class Epi>
; __device__ __forceinline__ void gemm_phase(LAS unsigned char* lds, const Gemm g, const StaticOrder& S, const Epi& E) {
;     ...
;     for (int i = 0; i < 2; ++i) { int R, C; stage_rc(tid * 16 + i * 8192, R, C); const int Rb = Epi::PERM ? ((R & ~31) + perm32(R & 31)) : R;
;         voffA[i] = (unsigned)(R * lda + C) * 2u; voffB[i] = (unsigned)(Rb * K + C) * 2u; }
;     const size_t kstep = (size_t)(BK * 2);
;     const size_t hstepA = (size_t)HALF * lda * 2, hstepB = (size_t)HALF * K * 2;
;     const size_t tstepA = 2 * hstepA, tstepB = 2 * hstepB;
;     const unsigned ldsw = (unsigned)wid * 1024u;
;     const int aoff = lds_byte(wr * 64 + fr, fq * 8), boff = lds_byte(wc * 32 + fr, fq * 8);
;     ...
;     PG8_STAGE(PG8_SB(0, 0), cB, voffB); PG8_STAGE(PG8_SA(0, 0), cA, voffA); PG8_STAGE(PG8_SB(0, 1), cB + hstepB, voffB); PG8_STAGE(PG8_SA(0, 1), cA + hstepA, voffA);
;     if (wr == 1) PG8_BAR;
;     PG8_WAIT_V(4); PG8_BAR;
;     PG8_STAGE(PG8_SB(1, 0), cB + kstep, voffB); PG8_STAGE(PG8_SA(1, 0), cA + kstep, voffA); PG8_STAGE(PG8_SB(1, 1), cB + hstepB + kstep, voffB);
;     PG8_WAIT_V(6); PG8_BAR;
;     for (;;) {
;         const bool has_next = S.next(ui + 1, nxt);
.LBB0_762:
	s_lshl_b32 s4, s4, 5
	s_and_b32 s12, s4, 0x60
	s_mov_b64 s[4:5], 0x80
	s_add_i32 m0, s19, 0x18000
	v_lshl_add_u64 v[6:7], v[6:7], 0, s[4:5]
	s_lshl_b32 s8, s1, 13
	s_lshl_b32 s13, s12, 7
	s_waitcnt vmcnt(4)
	s_barrier
	global_load_lds_dwordx4 v[6:7], off
	v_lshl_add_u64 v[4:5], v[4:5], 0, s[4:5]
	s_add_i32 m0, s19, 0x1a000
	s_add_i32 s35, s19, 0x8000
	s_add_i32 s36, s19, 0xa000
	global_load_lds_dwordx4 v[4:5], off
	v_lshl_add_u64 v[2:3], v[2:3], 0, s[4:5]
	s_mov_b32 m0, s35
	s_add_u32 s10, s22, 0x40080
	global_load_lds_dwordx4 v[2:3], off
	v_lshl_add_u64 v[0:1], v[0:1], 0, s[4:5]
	s_mov_b32 m0, s36
	s_addc_u32 s11, s23, 0
	global_load_lds_dwordx4 v[0:1], off
	s_add_i32 m0, s19, 0x1c000
	v_lshl_add_u64 v[0:1], s[10:11], 0, v[130:131]
	global_load_lds_dwordx4 v[0:1], off
	v_lshl_add_u64 v[0:1], s[10:11], 0, v[134:135]
	s_add_i32 m0, s19, 0x1e000
	v_bfe_u32 v2, v152, 4, 2
	global_load_lds_dwordx4 v[0:1], off
	v_and_b32_e32 v1, 15, v152
	v_lshlrev_b32_e32 v0, 4, v2
	v_lshlrev_b32_e32 v3, 2, v152
	v_lshl_or_b32 v174, s1, 6, v1
	v_lshl_or_b32 v1, v1, 6, v0
	v_and_b32_e32 v3, 32, v3
	s_sext_i32_i8 s40, s0
	v_bitop3_b32 v4, v1, s8, v3 bitop3:0xde
	v_lshlrev_b32_e32 v1, 6, v152
	s_movk_i32 s0, 0x3c0
	v_and_or_b32 v1, v1, s0, v0
	v_bitop3_b32 v175, s13, v1, v3 bitop3:0xf6
	v_mov_b32_e32 v1, v131
	v_lshl_add_u64 v[136:137], s[6:7], 0, v[0:1]
	v_lshlrev_b32_e32 v0, 8, v152
	v_and_b32_e32 v0, 0x38000, v0
	v_lshlrev_b32_e32 v1, 11, v10
	v_or3_b32 v0, v8, v0, v1
	v_add_u32_e32 v138, v0, v9
	v_lshlrev_b32_e32 v0, 4, v11
	v_and_b32_e32 v0, 0x78000, v0
	s_waitcnt vmcnt(6)
	v_or3_b32 v0, v8, v0, v1
	v_add_u32_e32 v140, v0, v9
	s_add_i32 s7, 0, 0x10000
	s_add_i32 s38, 0, 0x14000
	v_mbcnt_lo_u32_b32 v0, -1, 0
	s_ashr_i32 s37, s92, 31
	v_lshl_or_b32 v176, v2, 3, s12
	v_mov_b32_e32 v139, v131
	v_mov_b32_e32 v141, v131
	v_mov_b64_e32 v[142:143], 0x1000
	v_mov_b64_e32 v[144:145], 0xfff
	v_add_u32_e32 v177, s7, v175
	v_add_u32_e32 v178, 0, v4
	v_add_u32_e32 v179, s38, v175
	v_mbcnt_hi_u32_b32 v180, -1, v0
	s_mov_b32 s6, 0x3a800000
	s_mov_b32 s8, 0x358637bd
	s_mov_b32 s39, 0x800000
	s_barrier
.LBB0_763:
	v_readfirstlane_b32 s98, v152
	s_nop 3
	s_cmp_ge_u32 s98, 0x100
	s_cbranch_scc0 .Lknf2_skip
	s_setprio 1
.Lknf2_skip:
	s_add_i32 s34, s34, 1
	s_mul_i32 s0, s34, s37
	s_mul_hi_u32 s1, s34, s92
	s_add_i32 s1, s1, s0
	s_mul_i32 s0, s34, s92
	s_add_u32 s14, s0, s93
	s_addc_u32 s15, s1, s26
	v_cmp_gt_i64_e64 s[0:1], s[14:15], v[144:145]
	s_and_b64 vcc, exec, s[0:1]
	s_cbranch_vccnz .LBB0_769
	s_lshr_b32 s10, s14, 3
	s_mov_b32 s13, 0
	s_sub_u32 s11, s10, 0x80
	s_cmp_ge_u32 s10, 0x80
	s_cselect_b32 s10, s11, s10
	s_addc_u32 s13, s13, 0
	s_sub_u32 s11, s10, 0x80
	s_cmp_ge_u32 s10, 0x80
	s_cselect_b32 s10, s11, s10
	s_addc_u32 s13, s13, 0
	s_sub_u32 s11, s10, 0x80
	s_cmp_ge_u32 s10, 0x80
	s_cselect_b32 s10, s11, s10
	s_addc_u32 s13, s13, 0
	s_and_b32 s12, s14, 7
	s_lshl_b32 s12, s12, 2
	s_add_i32 s12, s12, s13
	s_lshl_b32 s12, s12, 3
	s_and_b32 s13, s10, 7
	s_add_i32 s12, s12, s13
	s_lshr_b32 s10, s10, 3

;     __device__ bool next(int i, Unit& u) const {
;         const long L = (long)i * G + c; if (L >= nwg) return false;
;         int wgid = (int)L; { const int q = nwg / NXCD, r = nwg % NXCD, xcd = wgid % NXCD, off = wgid / NXCD; wgid = (xcd < r ? xcd * (q + 1) : r * (q + 1) + (xcd - r) * q) + off; }
;         const int nig = WGM * nN, gid = wgid / nig, fm = gid * WGM, gsz = (nM - fm) < WGM ? (nM - fm) : WGM;
;         u.pm = fm + ((wgid % nig) % gsz); u.pn = (wgid % nig) / gsz; return true;
;     }
; template <class Epi>
; __device__ __forceinline__ void gemm_phase(LAS unsigned char* lds, const Gemm g, const StaticOrder& S, const Epi& E) {
;     ...
;         const bool has_next = S.next(ui + 1, nxt);
;         const char* nA = has_next ? (const char*)g.A + (size_t)nxt.pm * tstepA : cA; const char* nB = has_next ? (const char*)g.Bt + (size_t)nxt.pn * tstepB : cB;
.LBB0_836:
	s_or_b64 exec, exec, s[22:23]
	s_and_b64 vcc, exec, s[2:3]
	s_mov_b32 s6, s14
	s_mov_b32 s8, s16
	s_mov_b64 s[24:25], s[20:21]
	s_mov_b64 s[22:23], s[18:19]
	s_cbranch_vccnz .LBB0_861
.LBB0_837:
	v_readfirstlane_b32 s98, v152
	s_nop 3
	s_cmp_ge_u32 s98, 0x100
	s_cbranch_scc0 .Lknf3_skip
	s_setprio 1
.Lknf3_skip:
	s_add_i32 s33, s33, 1
	s_mul_i32 s2, s33, s40
	s_mul_hi_u32 s3, s33, s92
	s_add_i32 s3, s3, s2
	s_mul_i32 s2, s33, s92
	s_add_u32 s18, s2, s93
	s_addc_u32 s19, s3, s41
	v_cmp_gt_i64_e64 s[2:3], s[18:19], v[168:169]
	s_and_b64 vcc, exec, s[2:3]
	s_cbranch_vccnz .LBB0_843
	s_lshr_b32 s14, s18, 3
	s_mov_b32 s17, 0
	s_sub_u32 s15, s14, 0x20
	s_cmp_ge_u32 s14, 0x20
	s_cselect_b32 s14, s15, s14
	s_addc_u32 s17, s17, 0
	s_sub_u32 s15, s14, 0x20
	s_cmp_ge_u32 s14, 0x20
	s_cselect_b32 s14, s15, s14
	s_addc_u32 s17, s17, 0
	s_sub_u32 s15, s14, 0x20
	s_cmp_ge_u32 s14, 0x20
	s_cselect_b32 s14, s15, s14
	s_addc_u32 s17, s17, 0
	s_and_b32 s16, s18, 7
	s_lshl_b32 s16, s16, 2
	s_add_i32 s16, s16, s17
	s_lshl_b32 s16, s16, 3
	s_and_b32 s17, s14, 7
	s_add_i32 s16, s16, s17
	s_lshr_b32 s14, s14, 3

; #define PG8_STAGE(bufoff, gbase, voff) do { _Pragma("unroll") for (int _i = 0; _i < 2; ++_i) \
;         __builtin_amdgcn_global_load_lds((const unsigned*)((const char*)(gbase) + (voff)[_i]), (LAS unsigned*)(lds + (bufoff) + ldsw + _i * 8192), 16, 0, 0); } while (0)
; #define PG8_WAIT_V(n) asm volatile("s_waitcnt vmcnt(" #n ")" ::: "memory")
; #define PG8_BAR __builtin_amdgcn_s_barrier()
; template <class Epi>
; __device__ __forceinline__ void gemm_phase(LAS unsigned char* lds, const Gemm g, const StaticOrder& S, const Epi& E) {
;     ...
;     for (int i = 0; i < 2; ++i) { int R, C; stage_rc(tid * 16 + i * 8192, R, C); const int Rb = Epi::PERM ? ((R & ~31) + perm32(R & 31)) : R;
;         voffA[i] = (unsigned)(R * lda + C) * 2u; voffB[i] = (unsigned)(Rb * K + C) * 2u; }
;     const size_t kstep = (size_t)(BK * 2);
;     const size_t hstepA = (size_t)HALF * lda * 2, hstepB = (size_t)HALF * K * 2;
;     const size_t tstepA = 2 * hstepA, tstepB = 2 * hstepB;
;     const unsigned ldsw = (unsigned)wid * 1024u;
;     const int aoff = lds_byte(wr * 64 + fr, fq * 8), boff = lds_byte(wc * 32 + fr, fq * 8);
;     ...
;     PG8_STAGE(PG8_SB(0, 0), cB, voffB); PG8_STAGE(PG8_SA(0, 0), cA, voffA); PG8_STAGE(PG8_SB(0, 1), cB + hstepB, voffB); PG8_STAGE(PG8_SA(0, 1), cA + hstepA, voffA);
;     if (wr == 1) PG8_BAR;
;     PG8_WAIT_V(4); PG8_BAR;
;     PG8_STAGE(PG8_SB(1, 0), cB + kstep, voffB); PG8_STAGE(PG8_SA(1, 0), cA + kstep, voffA); PG8_STAGE(PG8_SB(1, 1), cB + hstepB + kstep, voffB);
;     PG8_WAIT_V(6); PG8_BAR;
;     for (;;) {
;         const bool has_next = S.next(ui + 1, nxt);
.LBB0_918:
	s_lshl_b32 s4, s4, 5
	s_and_b32 s8, s4, 0x60
	s_mov_b64 s[4:5], 0x80
	s_add_i32 m0, s19, 0x18000
	v_lshl_add_u64 v[6:7], v[6:7], 0, s[4:5]
	s_lshl_b32 s6, s1, 13
	s_lshl_b32 s12, s8, 7
	s_waitcnt vmcnt(4)
	s_barrier
	global_load_lds_dwordx4 v[6:7], off
	v_lshl_add_u64 v[4:5], v[4:5], 0, s[4:5]
	s_add_i32 m0, s19, 0x1a000
	s_add_i32 s35, s19, 0x8000
	s_add_i32 s36, s19, 0xa000
	global_load_lds_dwordx4 v[4:5], off
	v_lshl_add_u64 v[2:3], v[2:3], 0, s[4:5]
	s_mov_b32 m0, s35
	s_add_u32 s10, s22, 0x40080
	global_load_lds_dwordx4 v[2:3], off
	v_lshl_add_u64 v[0:1], v[0:1], 0, s[4:5]
	s_mov_b32 m0, s36
	s_addc_u32 s11, s23, 0
	global_load_lds_dwordx4 v[0:1], off
	s_add_i32 m0, s19, 0x1c000
	v_lshl_add_u64 v[0:1], s[10:11], 0, v[132:133]
	global_load_lds_dwordx4 v[0:1], off
	v_lshl_add_u64 v[0:1], s[10:11], 0, v[128:129]
	s_add_i32 m0, s19, 0x1e000
	v_bfe_u32 v2, v152, 4, 2
	global_load_lds_dwordx4 v[0:1], off
	v_and_b32_e32 v1, 15, v152
	v_lshlrev_b32_e32 v0, 4, v2
	v_lshlrev_b32_e32 v3, 2, v152
	v_lshl_or_b32 v170, s1, 6, v1
	v_lshl_or_b32 v1, v1, 6, v0
	v_and_b32_e32 v3, 32, v3
	s_sext_i32_i16 s42, s0
	v_bitop3_b32 v4, v1, s6, v3 bitop3:0xde
	v_lshlrev_b32_e32 v1, 6, v152
	s_movk_i32 s0, 0x3c0
	v_and_or_b32 v1, v1, s0, v0
	v_bitop3_b32 v171, s12, v1, v3 bitop3:0xf6
	v_mov_b32_e32 v1, v133
	v_lshl_add_u64 v[0:1], s[74:75], 0, v[0:1]
	s_mov_b64 s[0:1], 0x3c7c4000
	v_lshl_add_u64 v[136:137], v[0:1], 0, s[0:1]
	v_lshlrev_b32_e32 v0, 8, v152
	v_and_b32_e32 v0, 0x38000, v0
	v_lshlrev_b32_e32 v1, 11, v11
	v_or3_b32 v0, v9, v0, v1
	v_add_u32_e32 v138, v0, v10
	v_lshlrev_b32_e32 v0, 4, v8
	v_and_b32_e32 v0, 0x78000, v0
	s_waitcnt vmcnt(6)
	v_or3_b32 v0, v9, v0, v1
	v_add_u32_e32 v140, v0, v10
	s_add_i32 s38, 0, 0x10000
	s_add_i32 s39, 0, 0x14000
	v_mbcnt_lo_u32_b32 v0, -1, 0
	s_ashr_i32 s37, s92, 31
	v_lshl_or_b32 v172, v2, 3, s8
	v_mov_b32_e32 v139, v133
	v_mov_b32_e32 v141, v133
	v_mov_b64_e32 v[142:143], 0x1400
	v_mov_b64_e32 v[144:145], 0x13ff
	v_add_u32_e32 v173, s38, v171
	v_add_u32_e32 v174, 0, v4
	v_add_u32_e32 v175, s39, v171
	v_mbcnt_hi_u32_b32 v176, -1, v0
	s_movk_i32 s40, 0x2800
	s_mov_b32 s6, 0x3a800000
	s_mov_b32 s8, 0x358637bd
	s_mov_b32 s41, 0x800000
	s_barrier
.LBB0_919:
	v_readfirstlane_b32 s98, v152
	s_nop 3
	s_cmp_ge_u32 s98, 0x100
	s_cbranch_scc0 .Lknf4_skip
	s_setprio 1
.Lknf4_skip:
	s_add_i32 s34, s34, 1
	s_mul_i32 s0, s34, s37
	s_mul_hi_u32 s1, s34, s92
	s_add_i32 s1, s1, s0
	s_mul_i32 s0, s34, s92
	s_add_u32 s14, s0, s93
	s_addc_u32 s15, s1, s28
	v_cmp_gt_i64_e64 s[0:1], s[14:15], v[144:145]
	s_and_b64 vcc, exec, s[0:1]
	s_cbranch_vccnz .LBB0_921
	s_lshr_b32 s10, s14, 3
	s_mov_b32 s13, 0
	s_sub_u32 s11, s10, 0xa0
	s_cmp_ge_u32 s10, 0xa0
	s_cselect_b32 s10, s11, s10
	s_addc_u32 s13, s13, 0
	s_sub_u32 s11, s10, 0xa0
	s_cmp_ge_u32 s10, 0xa0
	s_cselect_b32 s10, s11, s10
	s_addc_u32 s13, s13, 0
	s_sub_u32 s11, s10, 0xa0
	s_cmp_ge_u32 s10, 0xa0
	s_cselect_b32 s10, s11, s10
	s_addc_u32 s13, s13, 0
	s_and_b32 s12, s14, 7
	s_lshl_b32 s12, s12, 2
	s_add_i32 s12, s12, s13
	s_lshl_b32 s12, s12, 3
	s_and_b32 s13, s10, 7
	s_add_i32 s12, s12, s13
	s_lshr_b32 s10, s10, 3

;     __device__ bool next(int i, Unit& u) const {
;         const long L = (long)i * G + c; if (L >= nwg) return false;
;         int wgid = (int)L; { const int q = nwg / NXCD, r = nwg % NXCD, xcd = wgid % NXCD, off = wgid / NXCD; wgid = (xcd < r ? xcd * (q + 1) : r * (q + 1) + (xcd - r) * q) + off; }
;         const int nig = WGM * nN, gid = wgid / nig, fm = gid * WGM, gsz = (nM - fm) < WGM ? (nM - fm) : WGM;
;         u.pm = fm + ((wgid % nig) % gsz); u.pn = (wgid % nig) / gsz; return true;
;     }
; template <class Epi>
; __device__ __forceinline__ void gemm_phase(LAS unsigned char* lds, const Gemm g, const StaticOrder& S, const Epi& E) {
;     ...
;         const bool has_next = S.next(ui + 1, nxt);
;         const char* nA = has_next ? (const char*)g.A + (size_t)nxt.pm * tstepA : cA; const char* nB = has_next ? (const char*)g.Bt + (size_t)nxt.pn * tstepB : cB;
.LBB0_1108:
	s_or_b64 exec, exec, s[4:5]
	s_and_b64 vcc, exec, s[2:3]
	s_mov_b32 s8, s16
	s_mov_b32 s10, s42
	s_mov_b64 s[22:23], s[20:21]
	s_mov_b64 s[24:25], s[18:19]
	s_cbranch_vccnz .LBB0_1135
.LBB0_1109:
	v_readfirstlane_b32 s98, v152
	s_nop 3
	s_cmp_ge_u32 s98, 0x100
	s_cbranch_scc0 .Lknf5_skip
	s_setprio 1
.Lknf5_skip:
	s_add_i32 s33, s33, 1
	s_mul_i32 s2, s33, s38
	s_mul_hi_u32 s3, s33, s92
	s_add_i32 s3, s3, s2
	s_mul_i32 s2, s33, s92
	s_add_u32 s18, s2, s93
	s_addc_u32 s19, s3, s39
	v_cmp_gt_i64_e64 s[2:3], s[18:19], v[168:169]
	v_cmp_lt_i64_e64 s[4:5], s[18:19], v[166:167]
	s_and_b64 vcc, exec, s[2:3]
	s_cbranch_vccnz .LBB0_1115
	s_ashr_i32 s16, s18, 31
	s_lshr_b32 s16, s16, 29
	s_add_i32 s19, s18, s16
	s_and_b32 s16, s19, -8
	s_sub_i32 s18, s18, s16
	s_cmp_gt_i32 s18, -1
	s_mov_b64 s[16:17], -1
	s_cbranch_scc0 .LBB0_1112
	s_lshl_b32 s20, s18, 7
	s_mov_b64 s[16:17], 0

; #define PG8_STAGE(bufoff, gbase, voff) do { _Pragma("unroll") for (int _i = 0; _i < 2; ++_i) \
;         __builtin_amdgcn_global_load_lds((const unsigned*)((const char*)(gbase) + (voff)[_i]), (LAS unsigned*)(lds + (bufoff) + ldsw + _i * 8192), 16, 0, 0); } while (0)
; #define PG8_WAIT_V(n) asm volatile("s_waitcnt vmcnt(" #n ")" ::: "memory")
; #define PG8_BAR __builtin_amdgcn_s_barrier()
; template <class Epi>
; __device__ __forceinline__ void gemm_phase(LAS unsigned char* lds, const Gemm g, const StaticOrder& S, const Epi& E) {
;     ...
;     for (int i = 0; i < 2; ++i) { int R, C; stage_rc(tid * 16 + i * 8192, R, C); const int Rb = Epi::PERM ? ((R & ~31) + perm32(R & 31)) : R;
;         voffA[i] = (unsigned)(R * lda + C) * 2u; voffB[i] = (unsigned)(Rb * K + C) * 2u; }
;     const size_t kstep = (size_t)(BK * 2);
;     const size_t hstepA = (size_t)HALF * lda * 2, hstepB = (size_t)HALF * K * 2;
;     const size_t tstepA = 2 * hstepA, tstepB = 2 * hstepB;
;     const unsigned ldsw = (unsigned)wid * 1024u;
;     const int aoff = lds_byte(wr * 64 + fr, fq * 8), boff = lds_byte(wc * 32 + fr, fq * 8);
;     ...
;     PG8_STAGE(PG8_SB(0, 0), cB, voffB); PG8_STAGE(PG8_SA(0, 0), cA, voffA); PG8_STAGE(PG8_SB(0, 1), cB + hstepB, voffB); PG8_STAGE(PG8_SA(0, 1), cA + hstepA, voffA);
;     if (wr == 1) PG8_BAR;
;     PG8_WAIT_V(4); PG8_BAR;
;     PG8_STAGE(PG8_SB(1, 0), cB + kstep, voffB); PG8_STAGE(PG8_SA(1, 0), cA + kstep, voffA); PG8_STAGE(PG8_SB(1, 1), cB + hstepB + kstep, voffB);
;     PG8_WAIT_V(6); PG8_BAR;
;     for (;;) {
;         const bool has_next = S.next(ui + 1, nxt);
.LBB0_1196:
	s_lshl_b32 s4, s4, 5
	s_and_b32 s8, s4, 0x60
	s_mov_b64 s[4:5], 0x80
	s_add_i32 m0, s19, 0x18000
	v_lshl_add_u64 v[6:7], v[6:7], 0, s[4:5]
	s_lshl_b32 s6, s1, 13
	s_lshl_b32 s12, s8, 7
	s_waitcnt vmcnt(4)
	s_barrier
	global_load_lds_dwordx4 v[6:7], off
	v_lshl_add_u64 v[4:5], v[4:5], 0, s[4:5]
	s_add_i32 m0, s19, 0x1a000
	s_add_i32 s34, s19, 0x8000
	s_add_i32 s35, s19, 0xa000
	global_load_lds_dwordx4 v[4:5], off
	v_lshl_add_u64 v[2:3], v[2:3], 0, s[4:5]
	s_mov_b32 m0, s34
	s_add_u32 s10, s22, 0x40080
	global_load_lds_dwordx4 v[2:3], off
	v_lshl_add_u64 v[0:1], v[0:1], 0, s[4:5]
	s_mov_b32 m0, s35
	s_addc_u32 s11, s23, 0
	global_load_lds_dwordx4 v[0:1], off
	s_add_i32 m0, s19, 0x1c000
	v_lshl_add_u64 v[0:1], s[10:11], 0, v[130:131]
	global_load_lds_dwordx4 v[0:1], off
	v_lshl_add_u64 v[0:1], s[10:11], 0, v[134:135]
	s_add_i32 m0, s19, 0x1e000
	v_bfe_u32 v2, v152, 4, 2
	global_load_lds_dwordx4 v[0:1], off
	v_and_b32_e32 v1, 15, v152
	v_lshlrev_b32_e32 v0, 4, v2
	v_lshlrev_b32_e32 v3, 2, v152
	v_lshl_or_b32 v153, s1, 6, v1
	v_lshl_or_b32 v1, v1, 6, v0
	v_and_b32_e32 v3, 32, v3
	s_sext_i32_i8 s40, s0
	v_bitop3_b32 v4, v1, s6, v3 bitop3:0xde
	v_lshlrev_b32_e32 v1, 6, v152
	s_movk_i32 s0, 0x3c0
	v_and_or_b32 v1, v1, s0, v0
	v_bitop3_b32 v174, s12, v1, v3 bitop3:0xf6
	v_mov_b32_e32 v1, v131
	v_lshl_add_u64 v[0:1], s[74:75], 0, v[0:1]
	s_mov_b64 s[0:1], 0x3cbc4000
	v_lshl_add_u64 v[136:137], v[0:1], 0, s[0:1]
	v_lshlrev_b32_e32 v0, 8, v152
	v_and_b32_e32 v0, 0x38000, v0
	v_lshlrev_b32_e32 v1, 11, v10
	v_or3_b32 v0, v8, v0, v1
	v_add_u32_e32 v138, v0, v9
	v_lshlrev_b32_e32 v0, 4, v11
	v_and_b32_e32 v0, 0x78000, v0
	s_waitcnt vmcnt(6)
	v_or3_b32 v0, v8, v0, v1
	v_add_u32_e32 v140, v0, v9
	s_add_i32 s37, 0, 0x10000
	s_add_i32 s38, 0, 0x14000
	v_mbcnt_lo_u32_b32 v0, -1, 0
	s_ashr_i32 s36, s92, 31
	v_lshl_or_b32 v175, v2, 3, s8
	v_mov_b32_e32 v139, v131
	v_mov_b32_e32 v141, v131
	v_mov_b64_e32 v[142:143], 0x1000
	v_mov_b64_e32 v[144:145], 0xfff
	v_add_u32_e32 v176, s37, v174
	v_add_u32_e32 v177, 0, v4
	v_add_u32_e32 v178, s38, v174
	v_mbcnt_hi_u32_b32 v179, -1, v0
	s_mov_b32 s6, 0x3a800000
	s_mov_b32 s8, 0x358637bd
	s_mov_b32 s39, 0x800000
	s_barrier
.LBB0_1197:
	v_readfirstlane_b32 s98, v152
	s_nop 3
	s_cmp_ge_u32 s98, 0x100
	s_cbranch_scc0 .Lknf6_skip
	s_setprio 1
.Lknf6_skip:
	s_add_i32 s33, s33, 1
	s_mul_i32 s0, s33, s36
	s_mul_hi_u32 s1, s33, s92
	s_add_i32 s1, s1, s0
	s_mul_i32 s0, s33, s92
	s_add_u32 s14, s0, s93
	s_addc_u32 s15, s1, s9
	v_cmp_gt_i64_e64 s[0:1], s[14:15], v[144:145]
	s_and_b64 vcc, exec, s[0:1]
	s_cbranch_vccnz .LBB0_1203
	s_lshr_b32 s10, s14, 3
	s_mov_b32 s13, 0
	s_sub_u32 s11, s10, 0x80
	s_cmp_ge_u32 s10, 0x80
	s_cselect_b32 s10, s11, s10
	s_addc_u32 s13, s13, 0
	s_sub_u32 s11, s10, 0x80
	s_cmp_ge_u32 s10, 0x80
	s_cselect_b32 s10, s11, s10
	s_addc_u32 s13, s13, 0
	s_sub_u32 s11, s10, 0x80
	s_cmp_ge_u32 s10, 0x80
	s_cselect_b32 s10, s11, s10
	s_addc_u32 s13, s13, 0
	s_and_b32 s12, s14, 7
	s_lshl_b32 s12, s12, 2
	s_add_i32 s12, s12, s13
	s_lshl_b32 s12, s12, 3
	s_and_b32 s13, s10, 7
	s_add_i32 s12, s12, s13
	s_lshr_b32 s10, s10, 3

;     __device__ bool next(int i, Unit& u) const {
;         const long L = (long)i * G + c; if (L >= nwg) return false;
;         int wgid = (int)L; { const int q = nwg / NXCD, r = nwg % NXCD, xcd = wgid % NXCD, off = wgid / NXCD; wgid = (xcd < r ? xcd * (q + 1) : r * (q + 1) + (xcd - r) * q) + off; }
;         const int nig = WGM * nN, gid = wgid / nig, fm = gid * WGM, gsz = (nM - fm) < WGM ? (nM - fm) : WGM;
;         u.pm = fm + ((wgid % nig) % gsz); u.pn = (wgid % nig) / gsz; return true;
;     }
; template <class Epi>
; __device__ __forceinline__ void gemm_phase(LAS unsigned char* lds, const Gemm g, const StaticOrder& S, const Epi& E) {
;     ...
;         const bool has_next = S.next(ui + 1, nxt);
;         const char* nA = has_next ? (const char*)g.A + (size_t)nxt.pm * tstepA : cA; const char* nB = has_next ? (const char*)g.Bt + (size_t)nxt.pn * tstepB : cB;
.LBB0_1270:
	s_or_b64 exec, exec, s[22:23]
	s_and_b64 vcc, exec, s[2:3]
	s_mov_b32 s6, s14
	s_mov_b32 s8, s16
	s_mov_b64 s[24:25], s[20:21]
	s_mov_b64 s[22:23], s[18:19]
	s_cbranch_vccnz .LBB0_1295
.LBB0_1271:
	v_readfirstlane_b32 s98, v152
	s_nop 3
	s_cmp_ge_u32 s98, 0x100
	s_cbranch_scc0 .Lknf7_skip
	s_setprio 1
.Lknf7_skip:
	s_add_i32 s33, s33, 1
	s_mul_i32 s2, s33, s40
	s_mul_hi_u32 s3, s33, s92
	s_add_i32 s3, s3, s2
	s_mul_i32 s2, s33, s92
	s_add_u32 s18, s2, s93
	s_addc_u32 s19, s3, s41
	v_cmp_gt_i64_e64 s[2:3], s[18:19], v[168:169]
	s_and_b64 vcc, exec, s[2:3]
	s_cbranch_vccnz .LBB0_1277
	s_lshr_b32 s14, s18, 3
	s_mov_b32 s17, 0
	s_sub_u32 s15, s14, 0x20
	s_cmp_ge_u32 s14, 0x20
	s_cselect_b32 s14, s15, s14
	s_addc_u32 s17, s17, 0
	s_sub_u32 s15, s14, 0x20
	s_cmp_ge_u32 s14, 0x20
	s_cselect_b32 s14, s15, s14
	s_addc_u32 s17, s17, 0
	s_sub_u32 s15, s14, 0x20
	s_cmp_ge_u32 s14, 0x20
	s_cselect_b32 s14, s15, s14
	s_addc_u32 s17, s17, 0
	s_and_b32 s16, s18, 7
	s_lshl_b32 s16, s16, 2
	s_add_i32 s16, s16, s17
	s_lshl_b32 s16, s16, 3
	s_and_b32 s17, s14, 7
	s_add_i32 s16, s16, s17
	s_lshr_b32 s14, s14, 3
